# grid barrier release flattened: every workgroup polls the top generation word; per-XCD release word dropped
# speedup vs baseline: 1.0070x; 1.0070x over previous
.LBB0_125:
	s_or_b64 exec, exec, s[10:11]
	v_cvt_f32_u32_e32 v5, v3
	s_waitcnt vmcnt(0)
	v_readfirstlane_b32 s3, v4
	v_sub_u32_e32 v4, 0, v3
	v_rcp_iflag_f32_e32 v5, v5
	v_add_u32_e32 v6, s3, v2
	v_mul_f32_e32 v5, 0x4f7ffffe, v5
	v_cvt_u32_f32_e32 v5, v5
	v_mul_lo_u32 v2, v4, v5
	v_mul_hi_u32 v2, v5, v2
	v_add_u32_e32 v2, v5, v2
	v_mul_hi_u32 v2, v6, v2
	v_mul_lo_u32 v4, v2, v3
	v_sub_u32_e32 v4, v6, v4
	v_add_u32_e32 v5, 1, v2
	v_sub_u32_e32 v7, v4, v3
	v_cmp_ge_u32_e32 vcc, v4, v3
	s_nop 1
	v_cndmask_b32_e32 v2, v2, v5, vcc
	v_cndmask_b32_e32 v4, v4, v7, vcc
	v_add_u32_e32 v5, 1, v2
	v_cmp_ge_u32_e32 vcc, v4, v3
	v_add_u32_e32 v4, 1, v6
	s_nop 0
	v_cndmask_b32_e32 v2, v2, v5, vcc
	v_mul_lo_u32 v5, v3, v2
	v_add_u32_e32 v3, v5, v3
	v_cmp_ne_u32_e32 vcc, v4, v3
	s_and_saveexec_b64 s[4:5], vcc
	s_xor_b64 s[10:11], exec, s[4:5]
	s_cbranch_execz .LBB0_139
	v_readlane_b32 s4, v254, 55
	s_waitcnt lgkmcnt(0)
	v_mov_b32_e32 v1, 0
	v_readlane_b32 s5, v254, 56
	s_nop 4
	global_load_dword v3, v1, s[4:5] sc1
	s_waitcnt vmcnt(0)
	v_cmp_eq_u32_e32 vcc, v3, v2
	s_and_saveexec_b64 s[12:13], vcc
	s_cbranch_execz .LBB0_138
	s_mov_b32 s3, 1
	s_mov_b64 s[14:15], 0
	s_branch .LBB0_129

.LBB0_131:
	v_readlane_b32 s4, v254, 55
	v_readlane_b32 s5, v254, 56
	s_add_i32 s3, s3, 1
	s_mov_b64 s[20:21], -1
	s_nop 2
	global_load_dword v3, v1, s[4:5] sc1
	s_waitcnt vmcnt(0)
	v_cmp_ne_u32_e32 vcc, v3, v2
	s_orn2_b64 s[18:19], vcc, exec
	s_branch .LBB0_128

.LBB0_156:
	s_or_b64 exec, exec, s[10:11]
	s_mov_b64 s[10:11], exec
	v_mbcnt_lo_u32_b32 v1, s10, 0
	v_mbcnt_hi_u32_b32 v1, s11, v1
	v_cmp_eq_u32_e32 vcc, 0, v1
	s_waitcnt vmcnt(0)
	buffer_inv sc1
	s_and_saveexec_b64 s[12:13], vcc
	s_cbranch_execz .LBB0_158
	s_bcnt1_i32_b64 s3, s[10:11]
	v_readlane_b32 s4, v254, 51
	v_mov_b32_e32 v1, 0
	v_mov_b32_e32 v2, s3
	v_readlane_b32 s5, v254, 52
	s_nop 4
.LBB0_158:
	s_or_b64 exec, exec, s[12:13]
	s_waitcnt vmcnt(0)

.LBB0_195:
	s_or_b64 exec, exec, s[8:9]
	v_cvt_f32_u32_e32 v5, v3
	s_waitcnt vmcnt(0)
	v_readfirstlane_b32 s5, v4
	v_sub_u32_e32 v4, 0, v3
	v_rcp_iflag_f32_e32 v5, v5
	v_add_u32_e32 v6, s5, v2
	v_mul_f32_e32 v5, 0x4f7ffffe, v5
	v_cvt_u32_f32_e32 v5, v5
	v_mul_lo_u32 v2, v4, v5
	v_mul_hi_u32 v2, v5, v2
	v_add_u32_e32 v2, v5, v2
	v_mul_hi_u32 v2, v6, v2
	v_mul_lo_u32 v4, v2, v3
	v_sub_u32_e32 v4, v6, v4
	v_add_u32_e32 v5, 1, v2
	v_sub_u32_e32 v7, v4, v3
	v_cmp_ge_u32_e32 vcc, v4, v3
	s_nop 1
	v_cndmask_b32_e32 v2, v2, v5, vcc
	v_cndmask_b32_e32 v4, v4, v7, vcc
	v_add_u32_e32 v5, 1, v2
	v_cmp_ge_u32_e32 vcc, v4, v3
	v_add_u32_e32 v4, 1, v6
	s_nop 0
	v_cndmask_b32_e32 v2, v2, v5, vcc
	v_mul_lo_u32 v5, v3, v2
	v_add_u32_e32 v3, v5, v3
	v_cmp_ne_u32_e32 vcc, v4, v3
	s_and_saveexec_b64 s[6:7], vcc
	s_xor_b64 s[8:9], exec, s[6:7]
	s_cbranch_execz .LBB0_209
	v_readlane_b32 s6, v254, 55
	s_waitcnt lgkmcnt(0)
	v_mov_b32_e32 v1, 0
	v_readlane_b32 s7, v254, 56
	s_nop 4
	global_load_dword v3, v1, s[6:7] sc1
	s_waitcnt vmcnt(0)
	v_cmp_eq_u32_e32 vcc, v3, v2
	s_and_saveexec_b64 s[10:11], vcc
	s_cbranch_execz .LBB0_208
	s_mov_b32 s5, 1
	s_mov_b64 s[12:13], 0
	s_branch .LBB0_199

.LBB0_201:
	v_readlane_b32 s6, v254, 55
	v_readlane_b32 s7, v254, 56
	s_add_i32 s5, s5, 1
	s_mov_b64 s[20:21], -1
	s_nop 2
	global_load_dword v3, v1, s[6:7] sc1
	s_waitcnt vmcnt(0)
	v_cmp_ne_u32_e32 vcc, v3, v2
	s_orn2_b64 s[18:19], vcc, exec
	s_branch .LBB0_198

.LBB0_226:
	s_or_b64 exec, exec, s[10:11]
	s_mov_b64 s[10:11], exec
	v_mbcnt_lo_u32_b32 v1, s10, 0
	v_mbcnt_hi_u32_b32 v1, s11, v1
	v_cmp_eq_u32_e32 vcc, 0, v1
	s_waitcnt vmcnt(0)
	buffer_inv sc1
	s_and_saveexec_b64 s[12:13], vcc
	s_cbranch_execz .LBB0_228
	s_bcnt1_i32_b64 s5, s[10:11]
	v_readlane_b32 s6, v254, 51
	v_mov_b32_e32 v1, 0
	v_mov_b32_e32 v2, s5
	v_readlane_b32 s7, v254, 52
	s_nop 4
.LBB0_228:
	s_or_b64 exec, exec, s[12:13]
	s_waitcnt vmcnt(0)

.LBB0_304:
	s_or_b64 exec, exec, s[36:37]
	v_cvt_f32_u32_e32 v6, v4
	s_waitcnt vmcnt(0)
	v_readfirstlane_b32 s9, v5
	v_sub_u32_e32 v5, 0, v4
	v_rcp_iflag_f32_e32 v6, v6
	v_add_u32_e32 v7, s9, v1
	v_mul_f32_e32 v6, 0x4f7ffffe, v6
	v_cvt_u32_f32_e32 v6, v6
	v_mul_lo_u32 v1, v5, v6
	v_mul_hi_u32 v1, v6, v1
	v_add_u32_e32 v1, v6, v1
	v_mul_hi_u32 v1, v7, v1
	v_mul_lo_u32 v5, v1, v4
	v_sub_u32_e32 v5, v7, v5
	v_add_u32_e32 v6, 1, v1
	v_cmp_ge_u32_e32 vcc, v5, v4
	s_nop 1
	v_cndmask_b32_e32 v1, v1, v6, vcc
	v_sub_u32_e32 v6, v5, v4
	v_cndmask_b32_e32 v5, v5, v6, vcc
	v_add_u32_e32 v6, 1, v1
	v_cmp_ge_u32_e32 vcc, v5, v4
	v_add_u32_e32 v5, 1, v7
	s_nop 0
	v_cndmask_b32_e32 v1, v1, v6, vcc
	v_mul_lo_u32 v6, v4, v1
	v_add_u32_e32 v4, v6, v4
	v_cmp_ne_u32_e32 vcc, v5, v4
	s_and_saveexec_b64 s[12:13], vcc
	s_xor_b64 s[36:37], exec, s[12:13]
	s_cbranch_execz .LBB0_318
	v_readlane_b32 s12, v254, 55
	v_readlane_b32 s13, v254, 56
	s_waitcnt lgkmcnt(0)
	s_nop 3
	global_load_dword v2, v3, s[12:13] sc1
	s_waitcnt vmcnt(0)
	v_cmp_eq_u32_e32 vcc, v2, v1
	s_and_saveexec_b64 s[58:59], vcc
	s_cbranch_execz .LBB0_317
	s_mov_b32 s9, 1
	s_mov_b64 s[68:69], 0
	s_branch .LBB0_308

.LBB0_335:
	s_or_b64 exec, exec, s[36:37]
	s_mov_b64 s[36:37], exec
	v_mbcnt_lo_u32_b32 v1, s36, 0
	v_mbcnt_hi_u32_b32 v1, s37, v1
	v_cmp_eq_u32_e32 vcc, 0, v1
	s_waitcnt vmcnt(0)
	buffer_inv sc1
	s_and_saveexec_b64 s[58:59], vcc
	s_cbranch_execz .LBB0_337
	s_bcnt1_i32_b64 s9, s[36:37]
	v_readlane_b32 s12, v254, 51
	v_mov_b32_e32 v1, s9
	v_readlane_b32 s13, v254, 52
	s_nop 4
.LBB0_337:
	s_or_b64 exec, exec, s[58:59]
	s_waitcnt vmcnt(0)

.LBB0_508:
	s_or_b64 exec, exec, s[36:37]
	s_mov_b64 s[36:37], exec
	v_mbcnt_lo_u32_b32 v1, s36, 0
	v_mbcnt_hi_u32_b32 v1, s37, v1
	v_cmp_eq_u32_e32 vcc, 0, v1
	s_waitcnt vmcnt(0)
	buffer_inv sc1
	s_and_saveexec_b64 s[58:59], vcc
	s_cbranch_execz .LBB0_510
	s_bcnt1_i32_b64 s9, s[36:37]
	v_readlane_b32 s12, v254, 51
	v_mov_b32_e32 v1, s9
	v_readlane_b32 s13, v254, 52
	s_nop 4
.LBB0_510:
	s_or_b64 exec, exec, s[58:59]
	s_waitcnt vmcnt(0)

.LBB0_576:
	s_or_b64 exec, exec, s[36:37]
	v_cvt_f32_u32_e32 v7, v5
	s_waitcnt vmcnt(0)
	v_readfirstlane_b32 s9, v6
	v_sub_u32_e32 v6, 0, v5
	v_rcp_iflag_f32_e32 v7, v7
	v_add_u32_e32 v8, s9, v2
	v_mul_f32_e32 v7, 0x4f7ffffe, v7
	v_cvt_u32_f32_e32 v7, v7
	v_mul_lo_u32 v2, v6, v7
	v_mul_hi_u32 v2, v7, v2
	v_add_u32_e32 v2, v7, v2
	v_mul_hi_u32 v2, v8, v2
	v_mul_lo_u32 v6, v2, v5
	v_sub_u32_e32 v6, v8, v6
	v_add_u32_e32 v7, 1, v2
	v_cmp_ge_u32_e32 vcc, v6, v5
	s_nop 1
	v_cndmask_b32_e32 v2, v2, v7, vcc
	v_sub_u32_e32 v7, v6, v5
	v_cndmask_b32_e32 v6, v6, v7, vcc
	v_add_u32_e32 v7, 1, v2
	v_cmp_ge_u32_e32 vcc, v6, v5
	v_add_u32_e32 v6, 1, v8
	s_nop 0
	v_cndmask_b32_e32 v2, v2, v7, vcc
	v_mul_lo_u32 v7, v5, v2
	v_add_u32_e32 v5, v7, v5
	v_cmp_ne_u32_e32 vcc, v6, v5
	s_and_saveexec_b64 s[12:13], vcc
	s_xor_b64 s[36:37], exec, s[12:13]
	s_cbranch_execz .LBB0_590
	v_readlane_b32 s12, v254, 55
	v_readlane_b32 s13, v254, 56
	s_waitcnt lgkmcnt(0)
	s_nop 3
	global_load_dword v4, v3, s[12:13] sc1
	s_waitcnt vmcnt(0)
	v_cmp_eq_u32_e32 vcc, v4, v2
	s_and_saveexec_b64 s[68:69], vcc
	s_cbranch_execz .LBB0_589
	s_mov_b32 s9, 1
	s_mov_b64 s[72:73], 0
	s_branch .LBB0_580

.LBB0_607:
	s_or_b64 exec, exec, s[36:37]
	s_mov_b64 s[36:37], exec
	v_mbcnt_lo_u32_b32 v2, s36, 0
	v_mbcnt_hi_u32_b32 v2, s37, v2
	v_cmp_eq_u32_e32 vcc, 0, v2
	s_waitcnt vmcnt(0)
	buffer_inv sc1
	s_and_saveexec_b64 s[68:69], vcc
	s_cbranch_execz .LBB0_609
	s_bcnt1_i32_b64 s9, s[36:37]
	v_readlane_b32 s12, v254, 51
	v_mov_b32_e32 v2, s9
	v_readlane_b32 s13, v254, 52
	s_nop 4
.LBB0_609:
	s_or_b64 exec, exec, s[68:69]
	s_waitcnt vmcnt(0)

.LBB0_651:
	s_or_b64 exec, exec, s[36:37]
	v_cvt_f32_u32_e32 v6, v4
	s_waitcnt vmcnt(0)
	v_readfirstlane_b32 s9, v5
	v_sub_u32_e32 v5, 0, v4
	v_rcp_iflag_f32_e32 v6, v6
	v_add_u32_e32 v7, s9, v1
	v_mul_f32_e32 v6, 0x4f7ffffe, v6
	v_cvt_u32_f32_e32 v6, v6
	v_mul_lo_u32 v1, v5, v6
	v_mul_hi_u32 v1, v6, v1
	v_add_u32_e32 v1, v6, v1
	v_mul_hi_u32 v1, v7, v1
	v_mul_lo_u32 v5, v1, v4
	v_sub_u32_e32 v5, v7, v5
	v_add_u32_e32 v6, 1, v1
	v_cmp_ge_u32_e32 vcc, v5, v4
	s_nop 1
	v_cndmask_b32_e32 v1, v1, v6, vcc
	v_sub_u32_e32 v6, v5, v4
	v_cndmask_b32_e32 v5, v5, v6, vcc
	v_add_u32_e32 v6, 1, v1
	v_cmp_ge_u32_e32 vcc, v5, v4
	v_add_u32_e32 v5, 1, v7
	s_nop 0
	v_cndmask_b32_e32 v1, v1, v6, vcc
	v_mul_lo_u32 v6, v4, v1
	v_add_u32_e32 v4, v6, v4
	v_cmp_ne_u32_e32 vcc, v5, v4
	s_and_saveexec_b64 s[12:13], vcc
	s_xor_b64 s[36:37], exec, s[12:13]
	s_cbranch_execz .LBB0_665
	v_readlane_b32 s12, v254, 55
	v_readlane_b32 s13, v254, 56
	s_waitcnt lgkmcnt(0)
	s_nop 3
	global_load_dword v2, v3, s[12:13] sc1
	s_waitcnt vmcnt(0)
	v_cmp_eq_u32_e32 vcc, v2, v1
	s_and_saveexec_b64 s[68:69], vcc
	s_cbranch_execz .LBB0_664
	s_mov_b32 s9, 1
	s_mov_b64 s[72:73], 0
	s_branch .LBB0_655

.LBB0_682:
	s_or_b64 exec, exec, s[36:37]
	s_mov_b64 s[36:37], exec
	v_mbcnt_lo_u32_b32 v1, s36, 0
	v_mbcnt_hi_u32_b32 v1, s37, v1
	v_cmp_eq_u32_e32 vcc, 0, v1
	s_waitcnt vmcnt(0)
	buffer_inv sc1
	s_and_saveexec_b64 s[68:69], vcc
	s_cbranch_execz .LBB0_684
	s_bcnt1_i32_b64 s9, s[36:37]
	v_readlane_b32 s12, v254, 51
	v_mov_b32_e32 v1, s9
	v_readlane_b32 s13, v254, 52
	s_nop 4
.LBB0_684:
	s_or_b64 exec, exec, s[68:69]
	s_waitcnt vmcnt(0)

.LBB0_719:
	s_or_b64 exec, exec, s[36:37]
	v_cvt_f32_u32_e32 v6, v4
	s_waitcnt vmcnt(0)
	v_readfirstlane_b32 s12, v5
	v_sub_u32_e32 v5, 0, v4
	v_rcp_iflag_f32_e32 v6, v6
	v_add_u32_e32 v7, s12, v1
	v_mul_f32_e32 v6, 0x4f7ffffe, v6
	v_cvt_u32_f32_e32 v6, v6
	v_mul_lo_u32 v1, v5, v6
	v_mul_hi_u32 v1, v6, v1
	v_add_u32_e32 v1, v6, v1
	v_mul_hi_u32 v1, v7, v1
	v_mul_lo_u32 v5, v1, v4
	v_sub_u32_e32 v5, v7, v5
	v_add_u32_e32 v6, 1, v1
	v_cmp_ge_u32_e32 vcc, v5, v4
	s_nop 1
	v_cndmask_b32_e32 v1, v1, v6, vcc
	v_sub_u32_e32 v6, v5, v4
	v_cndmask_b32_e32 v5, v5, v6, vcc
	v_add_u32_e32 v6, 1, v1
	v_cmp_ge_u32_e32 vcc, v5, v4
	v_add_u32_e32 v5, 1, v7
	s_nop 0
	v_cndmask_b32_e32 v1, v1, v6, vcc
	v_mul_lo_u32 v6, v4, v1
	v_add_u32_e32 v4, v6, v4
	v_cmp_ne_u32_e32 vcc, v5, v4
	s_and_saveexec_b64 s[12:13], vcc
	s_xor_b64 s[36:37], exec, s[12:13]
	s_cbranch_execz .LBB0_733
	v_readlane_b32 s12, v254, 55
	v_readlane_b32 s13, v254, 56
	s_waitcnt lgkmcnt(0)
	s_nop 3
	global_load_dword v2, v3, s[12:13] sc1
	s_waitcnt vmcnt(0)
	v_cmp_eq_u32_e32 vcc, v2, v1
	s_and_saveexec_b64 s[68:69], vcc
	s_cbranch_execz .LBB0_732
	s_mov_b32 s12, 1
	s_mov_b64 s[72:73], 0
	s_branch .LBB0_723

.LBB0_750:
	s_or_b64 exec, exec, s[36:37]
	s_mov_b64 s[36:37], exec
	v_mbcnt_lo_u32_b32 v1, s36, 0
	v_mbcnt_hi_u32_b32 v1, s37, v1
	v_cmp_eq_u32_e32 vcc, 0, v1
	s_waitcnt vmcnt(0)
	buffer_inv sc1
	s_and_saveexec_b64 s[68:69], vcc
	s_cbranch_execz .LBB0_752
	s_bcnt1_i32_b64 s12, s[36:37]
	v_mov_b32_e32 v1, s12
	v_readlane_b32 s12, v254, 51
	v_readlane_b32 s13, v254, 52
	s_nop 4
.LBB0_752:
	s_or_b64 exec, exec, s[68:69]
	s_waitcnt vmcnt(0)

.LBB0_820:
	s_or_b64 exec, exec, s[58:59]
	v_cvt_f32_u32_e32 v7, v5
	s_waitcnt vmcnt(0)
	v_readfirstlane_b32 s12, v6
	v_sub_u32_e32 v6, 0, v5
	v_rcp_iflag_f32_e32 v7, v7
	v_add_u32_e32 v8, s12, v2
	v_mul_f32_e32 v7, 0x4f7ffffe, v7
	v_cvt_u32_f32_e32 v7, v7
	v_mul_lo_u32 v2, v6, v7
	v_mul_hi_u32 v2, v7, v2
	v_add_u32_e32 v2, v7, v2
	v_mul_hi_u32 v2, v8, v2
	v_mul_lo_u32 v6, v2, v5
	v_sub_u32_e32 v6, v8, v6
	v_add_u32_e32 v7, 1, v2
	v_cmp_ge_u32_e32 vcc, v6, v5
	s_nop 1
	v_cndmask_b32_e32 v2, v2, v7, vcc
	v_sub_u32_e32 v7, v6, v5
	v_cndmask_b32_e32 v6, v6, v7, vcc
	v_add_u32_e32 v7, 1, v2
	v_cmp_ge_u32_e32 vcc, v6, v5
	v_add_u32_e32 v6, 1, v8
	s_nop 0
	v_cndmask_b32_e32 v2, v2, v7, vcc
	v_mul_lo_u32 v7, v5, v2
	v_add_u32_e32 v5, v7, v5
	v_cmp_ne_u32_e32 vcc, v6, v5
	s_and_saveexec_b64 s[12:13], vcc
	s_xor_b64 s[58:59], exec, s[12:13]
	s_cbranch_execz .LBB0_834
	v_readlane_b32 s12, v254, 55
	v_readlane_b32 s13, v254, 56
	s_waitcnt lgkmcnt(0)
	s_nop 3
	global_load_dword v4, v3, s[12:13] sc1
	s_waitcnt vmcnt(0)
	v_cmp_eq_u32_e32 vcc, v4, v2
	s_and_saveexec_b64 s[68:69], vcc
	s_cbranch_execz .LBB0_833
	s_mov_b32 s12, 1
	s_mov_b64 s[72:73], 0
	s_branch .LBB0_824

.LBB0_851:
	s_or_b64 exec, exec, s[58:59]
	s_mov_b64 s[58:59], exec
	v_mbcnt_lo_u32_b32 v2, s58, 0
	v_mbcnt_hi_u32_b32 v2, s59, v2
	v_cmp_eq_u32_e32 vcc, 0, v2
	s_waitcnt vmcnt(0)
	buffer_inv sc1
	s_and_saveexec_b64 s[68:69], vcc
	s_cbranch_execz .LBB0_853
	s_bcnt1_i32_b64 s12, s[58:59]
	v_mov_b32_e32 v2, s12
	v_readlane_b32 s12, v254, 51
	v_readlane_b32 s13, v254, 52
	s_nop 4
.LBB0_853:
	s_or_b64 exec, exec, s[68:69]
	s_waitcnt vmcnt(0)

.LBB0_879:
	s_or_b64 exec, exec, s[58:59]
	v_cvt_f32_u32_e32 v6, v4
	s_waitcnt vmcnt(0)
	v_readfirstlane_b32 s12, v5
	v_sub_u32_e32 v5, 0, v4
	v_rcp_iflag_f32_e32 v6, v6
	v_add_u32_e32 v7, s12, v1
	v_mul_f32_e32 v6, 0x4f7ffffe, v6
	v_cvt_u32_f32_e32 v6, v6
	v_mul_lo_u32 v1, v5, v6
	v_mul_hi_u32 v1, v6, v1
	v_add_u32_e32 v1, v6, v1
	v_mul_hi_u32 v1, v7, v1
	v_mul_lo_u32 v5, v1, v4
	v_sub_u32_e32 v5, v7, v5
	v_add_u32_e32 v6, 1, v1
	v_cmp_ge_u32_e32 vcc, v5, v4
	s_nop 1
	v_cndmask_b32_e32 v1, v1, v6, vcc
	v_sub_u32_e32 v6, v5, v4
	v_cndmask_b32_e32 v5, v5, v6, vcc
	v_add_u32_e32 v6, 1, v1
	v_cmp_ge_u32_e32 vcc, v5, v4
	v_add_u32_e32 v5, 1, v7
	s_nop 0
	v_cndmask_b32_e32 v1, v1, v6, vcc
	v_mul_lo_u32 v6, v4, v1
	v_add_u32_e32 v4, v6, v4
	v_cmp_ne_u32_e32 vcc, v5, v4
	s_and_saveexec_b64 s[12:13], vcc
	s_xor_b64 s[58:59], exec, s[12:13]
	s_cbranch_execz .LBB0_893
	v_readlane_b32 s12, v254, 55
	v_readlane_b32 s13, v254, 56
	s_waitcnt lgkmcnt(0)
	s_nop 3
	global_load_dword v2, v3, s[12:13] sc1
	s_waitcnt vmcnt(0)
	v_cmp_eq_u32_e32 vcc, v2, v1
	s_and_saveexec_b64 s[68:69], vcc
	s_cbranch_execz .LBB0_892
	s_mov_b32 s12, 1
	s_mov_b64 s[72:73], 0
	s_branch .LBB0_883

.LBB0_910:
	s_or_b64 exec, exec, s[58:59]
	s_mov_b64 s[58:59], exec
	v_mbcnt_lo_u32_b32 v1, s58, 0
	v_mbcnt_hi_u32_b32 v1, s59, v1
	v_cmp_eq_u32_e32 vcc, 0, v1
	s_waitcnt vmcnt(0)
	buffer_inv sc1
	s_and_saveexec_b64 s[68:69], vcc
	s_cbranch_execz .LBB0_912
	s_bcnt1_i32_b64 s12, s[58:59]
	v_mov_b32_e32 v1, s12
	v_readlane_b32 s12, v254, 51
	v_readlane_b32 s13, v254, 52
	s_nop 4
.LBB0_912:
	s_or_b64 exec, exec, s[68:69]
	s_waitcnt vmcnt(0)

.LBB0_963:
	s_or_b64 exec, exec, s[36:37]
	v_cvt_f32_u32_e32 v7, v5
	s_waitcnt vmcnt(0)
	v_readfirstlane_b32 s13, v6
	v_sub_u32_e32 v6, 0, v5
	v_rcp_iflag_f32_e32 v7, v7
	v_add_u32_e32 v8, s13, v2
	v_mul_f32_e32 v7, 0x4f7ffffe, v7
	v_cvt_u32_f32_e32 v7, v7
	v_mul_lo_u32 v2, v6, v7
	v_mul_hi_u32 v2, v7, v2
	v_add_u32_e32 v2, v7, v2
	v_mul_hi_u32 v2, v8, v2
	v_mul_lo_u32 v6, v2, v5
	v_sub_u32_e32 v6, v8, v6
	v_add_u32_e32 v7, 1, v2
	v_cmp_ge_u32_e32 vcc, v6, v5
	s_nop 1
	v_cndmask_b32_e32 v2, v2, v7, vcc
	v_sub_u32_e32 v7, v6, v5
	v_cndmask_b32_e32 v6, v6, v7, vcc
	v_add_u32_e32 v7, 1, v2
	v_cmp_ge_u32_e32 vcc, v6, v5
	v_add_u32_e32 v6, 1, v8
	s_nop 0
	v_cndmask_b32_e32 v2, v2, v7, vcc
	v_mul_lo_u32 v7, v5, v2
	v_add_u32_e32 v5, v7, v5
	v_cmp_ne_u32_e32 vcc, v6, v5
	s_and_saveexec_b64 s[16:17], vcc
	s_xor_b64 s[36:37], exec, s[16:17]
	s_cbranch_execz .LBB0_977
	v_readlane_b32 s16, v254, 55
	v_readlane_b32 s17, v254, 56
	s_waitcnt lgkmcnt(0)
	s_nop 3
	global_load_dword v4, v3, s[16:17] sc1
	s_waitcnt vmcnt(0)
	v_cmp_eq_u32_e32 vcc, v4, v2
	s_and_saveexec_b64 s[58:59], vcc
	s_cbranch_execz .LBB0_976
	s_mov_b32 s13, 1
	s_mov_b64 s[68:69], 0
	s_branch .LBB0_967

.LBB0_994:
	s_or_b64 exec, exec, s[36:37]
	s_mov_b64 s[36:37], exec
	v_mbcnt_lo_u32_b32 v2, s36, 0
	v_mbcnt_hi_u32_b32 v2, s37, v2
	v_cmp_eq_u32_e32 vcc, 0, v2
	s_waitcnt vmcnt(0)
	buffer_inv sc1
	s_and_saveexec_b64 s[58:59], vcc
	s_cbranch_execz .LBB0_996
	s_bcnt1_i32_b64 s13, s[36:37]
	v_readlane_b32 s16, v254, 51
	v_mov_b32_e32 v2, s13
	v_readlane_b32 s17, v254, 52
	s_nop 4
.LBB0_996:
	s_or_b64 exec, exec, s[58:59]
	s_waitcnt vmcnt(0)
